# plus chunk scan: counted LDS waits (each MFMA group waits lgkmcnt(8), all but the newest fragment batch, instead of alternating lgkmcnt(0) / none)
# speedup vs baseline: 1.0532x; 1.0001x over previous
; #define MFMA16(a, b, c) __builtin_amdgcn_mfma_f32_16x16x32_bf16(a, b, c, 0, 0, 0)
; #define PIN8(f) asm volatile("" : "+v"(f[0]), "+v"(f[1]), "+v"(f[2]), "+v"(f[3]), "+v"(f[4]), "+v"(f[5]), "+v"(f[6]), "+v"(f[7])); __builtin_amdgcn_sched_barrier(0)
; template <class RecFn>
; __device__ __forceinline__ void gdn_scan(LAS unsigned char* lds, int bh, int b0, RecFn rec_of, const float* gtarr, bf16_t* zb, const float* gnorm_w, float* Sout, const unsigned* late_cnt, unsigned late_need, int cwait) {
;     ...
;         bf16x8 Sb[4];
; #pragma unroll
;         for (int s2 = 0; s2 < 4; ++s2) Sb[s2] = pack8(S[2 * s2], S[2 * s2 + 1]);
;     ...
;         f32x4 av[4], ao[4];
;         bf16x8 fa[8], fb[8];
; #pragma unroll
;         for (int s2 = 0; s2 < 4; ++s2) { fa[s2] = LDF(REC_WN + (0 * 4 + s2) * 1024); fa[4 + s2] = LDF(REC_QD + (0 * 4 + s2) * 1024); }
; #pragma unroll
;         for (int rt = 0; rt < 4; ++rt) {
;             av[rt] = (f32x4){__uint_as_float(Uc[rt].x << 16), __uint_as_float(Uc[rt].x & 0xffff0000u), __uint_as_float(Uc[rt].y << 16), __uint_as_float(Uc[rt].y & 0xffff0000u)};
;             ao[rt] = z4;
;             bf16x8 (&cur)[8] = (rt & 1) ? fb : fa; bf16x8 (&nxt)[8] = (rt & 1) ? fa : fb;
;             if (rt < 3) {
; #pragma unroll
;                 for (int s2 = 0; s2 < 4; ++s2) { nxt[s2] = LDF(REC_WN + ((rt + 1) * 4 + s2) * 1024); nxt[4 + s2] = LDF(REC_QD + ((rt + 1) * 4 + s2) * 1024); }
;             } else {
; #pragma unroll
;                 for (int q = 0; q < 8; ++q) nxt[q] = LDF(REC_AM + q * 1024);
;             }
;             PIN8(cur);
; #pragma unroll
;             for (int s2 = 0; s2 < 4; ++s2) { av[rt] = MFMA16(cur[s2], Sb[s2], av[rt]); ao[rt] = MFMA16(cur[4 + s2], Sb[s2], ao[rt]); }
;             __builtin_amdgcn_sched_barrier(0);
;         }
.LBB0_786:
	s_and_b32 s22, s31, 1
	s_mul_i32 s23, s22, 0xe000
	v_add_u32_e32 v214, s23, v132
	ds_read_b128 v[108:111], v214 offset:19456
	ds_read_b128 v[134:137], v214 offset:18432
	ds_read_b128 v[138:141], v214 offset:3072
	ds_read_b128 v[142:145], v214 offset:2048
	ds_read_b128 v[146:149], v214 offset:17408
	ds_read_b128 v[150:153], v214 offset:16384
	ds_read_b128 v[154:157], v214 offset:1024
	ds_read_b128 v[158:161], v214
	ds_read_b128 v[162:165], v214 offset:23552
	ds_read_b128 v[166:169], v214 offset:22528
	ds_read_b128 v[170:173], v214 offset:7168
	ds_read_b128 v[174:177], v214 offset:6144
	ds_read_b128 v[178:181], v214 offset:21504
	ds_read_b128 v[182:185], v214 offset:20480
	ds_read_b128 v[186:189], v214 offset:5120
	ds_read_b128 v[190:193], v214 offset:4096
	v_cvt_pk_bf16_f32 v52, v30, v31
	v_cvt_pk_bf16_f32 v53, v32, v33
	v_cvt_pk_bf16_f32 v54, v26, v27
	v_cvt_pk_bf16_f32 v55, v28, v29
	v_cvt_pk_bf16_f32 v56, v22, v23
	v_cvt_pk_bf16_f32 v57, v24, v25
	v_cvt_pk_bf16_f32 v58, v2, v3
	v_cvt_pk_bf16_f32 v59, v4, v5
	v_cvt_pk_bf16_f32 v96, v10, v11
	v_cvt_pk_bf16_f32 v97, v12, v13
	v_cvt_pk_bf16_f32 v98, v18, v19
	v_cvt_pk_bf16_f32 v99, v20, v21
	v_cvt_pk_bf16_f32 v100, v14, v15
	v_cvt_pk_bf16_f32 v101, v16, v17
	v_cvt_pk_bf16_f32 v102, v6, v7
	v_cvt_pk_bf16_f32 v103, v8, v9
	v_lshlrev_b32_e32 v104, 16, v86
	v_and_b32_e32 v105, 0xffff0000, v86
	v_lshlrev_b32_e32 v106, 16, v87
	v_and_b32_e32 v107, 0xffff0000, v87
	s_waitcnt lgkmcnt(8)
	s_nop 0
	v_mfma_f32_16x16x32_bf16 v[104:107], v[158:161], v[52:55], v[104:107]
	v_mfma_f32_16x16x32_bf16 v[150:153], v[150:153], v[52:55], 0
	v_mfma_f32_16x16x32_bf16 v[104:107], v[154:157], v[56:59], v[104:107]
	v_mfma_f32_16x16x32_bf16 v[146:149], v[146:149], v[56:59], v[150:153]
	v_mfma_f32_16x16x32_bf16 v[104:107], v[142:145], v[96:99], v[104:107]
	v_mfma_f32_16x16x32_bf16 v[134:137], v[134:137], v[96:99], v[146:149]
	v_mfma_f32_16x16x32_bf16 v[104:107], v[138:141], v[100:103], v[104:107]
	v_mfma_f32_16x16x32_bf16 v[108:111], v[108:111], v[100:103], v[134:137]
	ds_read_b128 v[138:141], v214 offset:27648
	ds_read_b128 v[142:145], v214 offset:26624
	s_nop 1
	ds_read_b128 v[146:149], v214 offset:11264
	ds_read_b128 v[150:153], v214 offset:10240
	ds_read_b128 v[154:157], v214 offset:25600
	ds_read_b128 v[158:161], v214 offset:24576
	ds_read_b128 v[194:197], v214 offset:9216
	ds_read_b128 v[198:201], v214 offset:8192
	v_lshlrev_b32_e32 v134, 16, v84
	v_and_b32_e32 v135, 0xffff0000, v84
	v_lshlrev_b32_e32 v136, 16, v85
	v_and_b32_e32 v137, 0xffff0000, v85
	s_nop 1
	s_waitcnt lgkmcnt(8)
	v_mfma_f32_16x16x32_bf16 v[84:87], v[190:193], v[52:55], v[134:137]
	v_mfma_f32_16x16x32_bf16 v[134:137], v[182:185], v[52:55], 0
	v_mfma_f32_16x16x32_bf16 v[84:87], v[186:189], v[56:59], v[84:87]
	v_mfma_f32_16x16x32_bf16 v[134:137], v[178:181], v[56:59], v[134:137]
	v_mfma_f32_16x16x32_bf16 v[84:87], v[174:177], v[96:99], v[84:87]
	v_mfma_f32_16x16x32_bf16 v[134:137], v[166:169], v[96:99], v[134:137]
	v_mfma_f32_16x16x32_bf16 v[84:87], v[170:173], v[100:103], v[84:87]
	v_mfma_f32_16x16x32_bf16 v[134:137], v[162:165], v[100:103], v[134:137]
	ds_read_b128 v[166:169], v214 offset:31744
	ds_read_b128 v[170:173], v214 offset:30720
	ds_read_b128 v[174:177], v214 offset:15360
	ds_read_b128 v[178:181], v214 offset:14336
	ds_read_b128 v[182:185], v214 offset:29696
	ds_read_b128 v[186:189], v214 offset:28672
	ds_read_b128 v[190:193], v214 offset:13312
	ds_read_b128 v[202:205], v214 offset:12288
	v_lshlrev_b32_e32 v162, 16, v82
	v_and_b32_e32 v163, 0xffff0000, v82
	v_lshlrev_b32_e32 v164, 16, v83
	v_and_b32_e32 v165, 0xffff0000, v83
	s_waitcnt lgkmcnt(8)
	s_nop 0
	v_mfma_f32_16x16x32_bf16 v[162:165], v[198:201], v[52:55], v[162:165]
	v_mfma_f32_16x16x32_bf16 v[158:161], v[158:161], v[52:55], 0
	v_mfma_f32_16x16x32_bf16 v[162:165], v[194:197], v[56:59], v[162:165]
	v_mfma_f32_16x16x32_bf16 v[154:157], v[154:157], v[56:59], v[158:161]
	v_mfma_f32_16x16x32_bf16 v[150:153], v[150:153], v[96:99], v[162:165]
	v_mfma_f32_16x16x32_bf16 v[142:145], v[142:145], v[96:99], v[154:157]
	v_mfma_f32_16x16x32_bf16 v[146:149], v[146:149], v[100:103], v[150:153]
	v_mfma_f32_16x16x32_bf16 v[138:141], v[138:141], v[100:103], v[142:145]
	s_nop 4
	ds_read_b128 v[150:153], v214 offset:49152
	ds_read_b128 v[154:157], v214 offset:50176
	ds_read_b128 v[158:161], v214 offset:51200
	ds_read_b128 v[162:165], v214 offset:52224
	ds_read_b128 v[194:197], v214 offset:53248
	ds_read_b128 v[198:201], v214 offset:54272
	ds_read_b128 v[206:209], v214 offset:55296
	ds_read_b128 v[210:213], v214 offset:56320
	v_lshlrev_b32_e32 v142, 16, v80
	v_and_b32_e32 v143, 0xffff0000, v80
	v_lshlrev_b32_e32 v144, 16, v81
	v_and_b32_e32 v145, 0xffff0000, v81
	s_nop 1
	s_waitcnt lgkmcnt(8)
; #define LAS __attribute__((address_space(3)))
; __device__ __forceinline__ unsigned cvt_pk_bf16(float lo, float hi) { const bf16x2_t r = __builtin_convertvector((f32x2){lo, hi}, bf16x2_t); return __builtin_bit_cast(unsigned, r); }
; #define MFMA16(a, b, c) __builtin_amdgcn_mfma_f32_16x16x32_bf16(a, b, c, 0, 0, 0)
; #define PIN8(f) asm volatile("" : "+v"(f[0]), "+v"(f[1]), "+v"(f[2]), "+v"(f[3]), "+v"(f[4]), "+v"(f[5]), "+v"(f[6]), "+v"(f[7])); __builtin_amdgcn_sched_barrier(0)
; template <class RecFn>
; __device__ __forceinline__ void gdn_scan(LAS unsigned char* lds, int bh, int b0, RecFn rec_of, const float* gtarr, bf16_t* zb, const float* gnorm_w, float* Sout, const unsigned* late_cnt, unsigned late_need, int cwait) {
;     ...
;         bf16x8 Vb[2];
; #pragma unroll
;         for (int s = 0; s < 2; ++s) Vb[s] = pack8(av[2 * s], av[2 * s + 1]);
; #pragma unroll
;         for (int q = 0; q < 8; ++q) fb[q] = LDF(REC_KDT + q * 1024);
;         PIN8(fa);
; #pragma unroll
;         for (int rt = 0; rt < 4; ++rt)
; #pragma unroll
;             for (int s = 0; s < 2; ++s) ao[rt] = MFMA16(fa[rt * 2 + s], Vb[s], ao[rt]);
;         __builtin_amdgcn_sched_barrier(0);
; #pragma unroll
;         for (int q = 0; q < 8; ++q) fa[q] = LDF(REC_KDT + (8 + q) * 1024);
;         PIN8(fb);
; #pragma unroll
;         for (int dt = 0; dt < 4; ++dt) { S[dt] = S[dt] * gt;
; #pragma unroll
;             for (int s = 0; s < 2; ++s) S[dt] = MFMA16(fb[dt * 2 + s], Vb[s], S[dt]); }
;         __builtin_amdgcn_sched_barrier(0);
;         PIN8(fa);
; #pragma unroll
;         for (int dt = 4; dt < 8; ++dt) { S[dt] = S[dt] * gt;
; #pragma unroll
;             for (int s = 0; s < 2; ++s) S[dt] = MFMA16(fa[(dt - 4) * 2 + s], Vb[s], S[dt]); }
;     ...
;         { LAS unsigned char* ost = lds + P3_OST + (c & 1) * P3_OSTB;
; #pragma unroll
;           for (int rt = 0; rt < 4; ++rt)
; #pragma unroll
;             for (int r = 0; r < 4; ++r) { const int i = 16 * rt + 4 * g + r; const float v = ao[rt][r];
;                 *(LAS bf16_t*)(ost + (i * 132 + 16 * wave + l15) * 2) = (bf16_t)(cvt_pk_bf16(v, 0.f) & 0xffffu); } }
;         asm volatile("s_waitcnt vmcnt(0)" ::: "memory");
;         __syncthreads();
	v_mfma_f32_16x16x32_bf16 v[80:83], v[202:205], v[52:55], v[142:145]
	v_mfma_f32_16x16x32_bf16 v[52:55], v[186:189], v[52:55], 0
	v_mfma_f32_16x16x32_bf16 v[80:83], v[190:193], v[56:59], v[80:83]
	v_mfma_f32_16x16x32_bf16 v[52:55], v[182:185], v[56:59], v[52:55]
	v_mfma_f32_16x16x32_bf16 v[56:59], v[178:181], v[96:99], v[80:83]
	v_mfma_f32_16x16x32_bf16 v[52:55], v[170:173], v[96:99], v[52:55]
	v_mfma_f32_16x16x32_bf16 v[56:59], v[174:177], v[100:103], v[56:59]
	v_mfma_f32_16x16x32_bf16 v[52:55], v[166:169], v[100:103], v[52:55]
	s_nop 2
	v_cvt_pk_bf16_f32 v80, v104, v105
	v_cvt_pk_bf16_f32 v81, v106, v107
	ds_read_b128 v[96:99], v214 offset:39936
	ds_read_b128 v[100:103], v214 offset:38912
	ds_read_b128 v[104:107], v214 offset:37888
	ds_read_b128 v[142:145], v214 offset:36864
	ds_read_b128 v[166:169], v214 offset:35840
	ds_read_b128 v[170:173], v214 offset:34816
	ds_read_b128 v[174:177], v214 offset:33792
	ds_read_b128 v[178:181], v214 offset:32768
	v_cvt_pk_bf16_f32 v82, v84, v85
	v_cvt_pk_bf16_f32 v83, v86, v87
	v_cvt_pk_bf16_f32 v84, v146, v147
	v_cvt_pk_bf16_f32 v85, v148, v149
	v_cvt_pk_bf16_f32 v86, v56, v57
	v_cvt_pk_bf16_f32 v87, v58, v59
	s_waitcnt lgkmcnt(8)
	s_nop 0
	v_mfma_f32_16x16x32_bf16 v[56:59], v[150:153], v[80:83], v[108:111]
	v_mfma_f32_16x16x32_bf16 v[108:111], v[158:161], v[80:83], v[134:137]
	v_mfma_f32_16x16x32_bf16 v[134:137], v[194:197], v[80:83], v[138:141]
	v_mfma_f32_16x16x32_bf16 v[52:55], v[206:209], v[80:83], v[52:55]
	v_mfma_f32_16x16x32_bf16 v[56:59], v[154:157], v[84:87], v[56:59]
	v_mfma_f32_16x16x32_bf16 v[108:111], v[162:165], v[84:87], v[108:111]
	v_mfma_f32_16x16x32_bf16 v[134:137], v[198:201], v[84:87], v[134:137]
	v_mfma_f32_16x16x32_bf16 v[52:55], v[210:213], v[84:87], v[52:55]
	ds_read_b128 v[138:141], v214 offset:48128
	ds_read_b128 v[146:149], v214 offset:47104
	ds_read_b128 v[150:153], v214 offset:46080
	ds_read_b128 v[154:157], v214 offset:45056
	ds_read_b128 v[158:161], v214 offset:44032
	ds_read_b128 v[162:165], v214 offset:43008
	ds_read_b128 v[182:185], v214 offset:41984
	ds_read_b128 v[186:189], v214 offset:40960
	v_pk_mul_f32 v[32:33], v[76:77], v[32:33] op_sel_hi:[0,1]
	v_pk_mul_f32 v[30:31], v[76:77], v[30:31] op_sel_hi:[0,1]
	v_pk_mul_f32 v[28:29], v[76:77], v[28:29] op_sel_hi:[0,1]
	v_pk_mul_f32 v[26:27], v[76:77], v[26:27] op_sel_hi:[0,1]
	v_pk_mul_f32 v[24:25], v[76:77], v[24:25] op_sel_hi:[0,1]
	v_pk_mul_f32 v[22:23], v[76:77], v[22:23] op_sel_hi:[0,1]
	v_pk_mul_f32 v[4:5], v[76:77], v[4:5] op_sel_hi:[0,1]
	v_pk_mul_f32 v[2:3], v[76:77], v[2:3] op_sel_hi:[0,1]
	s_waitcnt lgkmcnt(8)
	v_mfma_f32_16x16x32_bf16 v[30:33], v[178:181], v[80:83], v[30:33]
	v_mfma_f32_16x16x32_bf16 v[26:29], v[170:173], v[80:83], v[26:29]
	v_mfma_f32_16x16x32_bf16 v[22:25], v[142:145], v[80:83], v[22:25]
	v_mfma_f32_16x16x32_bf16 v[2:5], v[100:103], v[80:83], v[2:5]
	v_mfma_f32_16x16x32_bf16 v[30:33], v[174:177], v[84:87], v[30:33]
	v_mfma_f32_16x16x32_bf16 v[26:29], v[166:169], v[84:87], v[26:29]
	v_mfma_f32_16x16x32_bf16 v[22:25], v[104:107], v[84:87], v[22:25]
	v_mfma_f32_16x16x32_bf16 v[2:5], v[96:99], v[84:87], v[2:5]
	s_waitcnt lgkmcnt(0)
	s_mulk_i32 s22, 0x4200
	s_add_i32 s22, s22, 0
	s_add_i32 s22, s22, 0x1c000
	v_pk_mul_f32 v[12:13], v[76:77], v[12:13] op_sel_hi:[0,1]
	v_pk_mul_f32 v[10:11], v[76:77], v[10:11] op_sel_hi:[0,1]
	v_pk_mul_f32 v[20:21], v[76:77], v[20:21] op_sel_hi:[0,1]
	v_pk_mul_f32 v[18:19], v[76:77], v[18:19] op_sel_hi:[0,1]
	v_pk_mul_f32 v[16:17], v[76:77], v[16:17] op_sel_hi:[0,1]
	v_pk_mul_f32 v[14:15], v[76:77], v[14:15] op_sel_hi:[0,1]
	v_pk_mul_f32 v[8:9], v[76:77], v[8:9] op_sel_hi:[0,1]
	v_pk_mul_f32 v[6:7], v[76:77], v[6:7] op_sel_hi:[0,1]
	v_cvt_pk_bf16_f32 v56, v56, s0
	v_add_u32_e32 v76, s22, v116
	ds_write_b16 v76, v56
	v_cvt_pk_bf16_f32 v56, v57, s0
	ds_write_b16 v76, v56 offset:264
	v_cvt_pk_bf16_f32 v56, v58, s0
	ds_write_b16 v76, v56 offset:528
	v_cvt_pk_bf16_f32 v56, v59, s0
	ds_write_b16 v76, v56 offset:792
	v_cvt_pk_bf16_f32 v56, v108, s0
	ds_write_b16 v76, v56 offset:4224
	v_cvt_pk_bf16_f32 v56, v109, s0
	ds_write_b16 v76, v56 offset:4488
	v_cvt_pk_bf16_f32 v56, v110, s0
	ds_write_b16 v76, v56 offset:4752
	v_cvt_pk_bf16_f32 v56, v111, s0
	ds_write_b16 v76, v56 offset:5016
	v_cvt_pk_bf16_f32 v56, v134, s0
	ds_write_b16 v76, v56 offset:8448
	v_cvt_pk_bf16_f32 v56, v135, s0
	ds_write_b16 v76, v56 offset:8712
	v_cvt_pk_bf16_f32 v56, v136, s0
	ds_write_b16 v76, v56 offset:8976
	v_cvt_pk_bf16_f32 v56, v137, s0
	v_mfma_f32_16x16x32_bf16 v[10:13], v[186:189], v[80:83], v[10:13]
	ds_write_b16 v76, v56 offset:9240
	v_cvt_pk_bf16_f32 v52, v52, s0
	v_mfma_f32_16x16x32_bf16 v[18:21], v[162:165], v[80:83], v[18:21]
	ds_write_b16 v76, v52 offset:12672
	v_cvt_pk_bf16_f32 v52, v53, s0
	v_mfma_f32_16x16x32_bf16 v[14:17], v[154:157], v[80:83], v[14:17]
	ds_write_b16 v76, v52 offset:12936
	v_cvt_pk_bf16_f32 v52, v54, s0
	v_mfma_f32_16x16x32_bf16 v[6:9], v[146:149], v[80:83], v[6:9]
	ds_write_b16 v76, v52 offset:13200
	v_cvt_pk_bf16_f32 v52, v55, s0
	v_mfma_f32_16x16x32_bf16 v[10:13], v[182:185], v[84:87], v[10:13]
	ds_write_b16 v76, v52 offset:13464
	s_waitcnt vmcnt(0)
	s_cmp_eq_u32 s30, 33
	v_mfma_f32_16x16x32_bf16 v[18:21], v[158:161], v[84:87], v[18:21]
	s_waitcnt vmcnt(0) lgkmcnt(0)
	s_barrier
	v_mfma_f32_16x16x32_bf16 v[14:17], v[150:153], v[84:87], v[14:17]
	v_mfma_f32_16x16x32_bf16 v[6:9], v[138:141], v[84:87], v[6:9]
	s_cbranch_scc1 .LBB0_788
	v_mov_b64_e32 v[58:59], v[42:43]
	v_mov_b64_e32 v[54:55], v[38:39]
	v_mov_b64_e32 v[86:87], v[88:89]
	v_mov_b64_e32 v[84:85], v[90:91]
	v_mov_b64_e32 v[82:83], v[92:93]
	v_mov_b64_e32 v[80:81], v[94:95]
	v_mov_b32_e32 v76, v34
	v_mov_b64_e32 v[56:57], v[40:41]
	v_mov_b64_e32 v[52:53], v[36:37]
	s_mov_b32 s31, s30
	s_branch .LBB0_763
